# adds mixer B: negm passed as MFMA C operand (no copies) and merged vmcnt ladder before LDS staging writes
# baseline (speedup 1.0000x reference)
; #define LAS __attribute__((address_space(3)))
; #define NAP_LOAD(T_) do { _Pragma("unroll") for (int j = 0; j < 8; ++j) { const int g_ = 8 * (T_) + j, kr_ = (g_ * 205) >> 10, kc_ = g_ - 5 * kr_; const size_t off_ = (size_t)(kr_ * 64 + kc_ * 8) * NEP; \
;                       kr[j] = *(const u32x4*)(kp + off_); vr[j] = *(const u32x4*)(vp + off_); } } while (0)
; __device__ __forceinline__ void qkt2(f32x16& p0, f32x16& p1, LAS const unsigned char* kslot, const bf16x8 (&qr)[4], const f32x16& negm, int r32, int hi) {
; #pragma unroll
;     for (int d0 = 0; d0 < 4; ++d0) {
;         LAS const unsigned char* kb = kslot + (2 * d0 + hi) * 1024 + ((r32 ^ (2 * d0 + hi)) * 16); asm volatile("" : "+v"(kb));
;         const bf16x8 b0 = *(LAS const bf16x8*)(kb);
;         const bf16x8 b1 = *(LAS const bf16x8*)(kb + 512);
;         if (d0 == 0) { p0 = __builtin_amdgcn_mfma_f32_32x32x16_bf16(b0, qr[0], negm, 0, 0, 0); p1 = __builtin_amdgcn_mfma_f32_32x32x16_bf16(b1, qr[0], negm, 0, 0, 0); }
;         else { p0 = __builtin_amdgcn_mfma_f32_32x32x16_bf16(b0, qr[d0], p0, 0, 0, 0); p1 = __builtin_amdgcn_mfma_f32_32x32x16_bf16(b1, qr[d0], p1, 0, 0, 0); }
;     }
; }
; __global__ void __launch_bounds__(NTHREADS) fwd_megakernel(Params P) {
;     ...
;                   NAP_LOAD(0);
;                   const int kcs = 4 * hi - cs;
;                   for (int jt = 0; jt < 5; ++jt) {
;                       LAS unsigned char* kw = wl + ch * 1024 + (lrow ^ ch) * 16; LAS unsigned char* vw = wl + 8192 + dhV * 4096 + lrowV * 64 + cwV * 16; asm volatile("" : "+v"(kw), "+v"(vw));
; #pragma unroll
;                       for (int j = 0; j < 8; ++j) { *(LAS u32x4*)(kw + j * 128) = kr[j]; *(LAS u32x4*)(vw + j * 512) = vr[j]; }
;                       int kcs_ = kcs; asm volatile("" : "+v"(kcs_));
;                       ModNAP mod; mod.kcs = kcs_; mod.tl = tabL + (15 - qc + 4 * hi);
; #pragma unroll
;                       for (int g = 0; g < 8; ++g) { const int g_ = 8 * jt + g, kr_ = (g_ * 205) >> 10, kc_ = g_ - 5 * kr_; mod.C8[g] = cbase + kc_ * 8; mod.U[g] = (h * 15 + (rs0 + kr_ - r + 7)) * 31 + cbase + kc_ * 8; }
;                       bf16x8 pa[4];
;                       if (jt + 1 < 5) NAP_LOAD(jt + 1);
;                       f32x16 s0, s1;
;                       qkt2(s0, s1, wl, qr, negm, r32, hi);
.LBB0_266:
	v_mov_b32_e32 v2, v187
	v_mov_b32_e32 v3, v185
	v_mov_b32_e32 v197, v209
	s_cmpk_eq_i32 s12, 0x19a0
	s_waitcnt vmcnt(8)
	ds_write_b128 v3, v[112:115]
	ds_write_b128 v2, v[116:119]
	ds_write_b128 v3, v[120:123] offset:128
	ds_write_b128 v2, v[124:127] offset:512
	ds_write_b128 v3, v[128:131] offset:256
	ds_write_b128 v2, v[132:135] offset:1024
	ds_write_b128 v3, v[136:139] offset:384
	ds_write_b128 v2, v[140:143] offset:1536
	s_waitcnt vmcnt(0)
	ds_write_b128 v3, v[144:147] offset:512
	ds_write_b128 v2, v[148:151] offset:2048
	ds_write_b128 v3, v[152:155] offset:640
	ds_write_b128 v2, v[156:159] offset:2560
	ds_write_b128 v3, v[160:163] offset:768
	ds_write_b128 v2, v[164:167] offset:3072
	ds_write_b128 v3, v[168:171] offset:896
	ds_write_b128 v2, v[172:175] offset:3584
	s_cbranch_scc1 .LBB0_268
	s_lshr_b32 s2, s10, 10
	s_mul_i32 s2, s2, 24
	s_add_i32 s33, s2, s13
	s_lshr_b32 s2, s16, 10
	s_mul_i32 s2, s2, 24
	s_add_i32 s34, s2, s13
	s_lshr_b32 s2, s17, 10
	s_mul_i32 s2, s2, 24
	s_add_i32 s35, s2, s13
	s_lshr_b32 s2, s18, 10
	s_mul_i32 s2, s2, 24
	s_add_i32 s36, s2, s13
	s_lshr_b32 s2, s19, 10
	s_mul_i32 s2, s2, 24
	s_add_i32 s37, s2, s13
	s_lshr_b32 s2, s20, 10
	s_mul_i32 s2, s2, 24
	s_add_i32 s38, s2, s13
	s_lshr_b32 s2, s21, 10
	s_mul_i32 s2, s2, 24
	s_add_i32 s39, s2, s13
	s_lshr_b32 s2, s24, 10
	s_mul_i32 s2, s2, 24
	s_add_i32 s2, s2, s13
	s_sub_i32 s42, s2, 56
	v_mad_i64_i32 v[2:3], s[2:3], s42, v227, v[200:201]
	s_sub_i32 s39, s39, 48
	v_mad_i64_i32 v[4:5], s[2:3], s42, v227, v[202:203]
	global_load_dwordx4 v[112:115], v[2:3], off offset:2560
	global_load_dwordx4 v[116:119], v[4:5], off offset:3584
	v_mad_i64_i32 v[2:3], s[2:3], s39, v227, v[200:201]
	s_sub_i32 s38, s38, 40
	v_mad_i64_i32 v[4:5], s[2:3], s39, v227, v[202:203]
	global_load_dwordx4 v[120:123], v[2:3], off offset:2560
	global_load_dwordx4 v[124:127], v[4:5], off offset:3584
	v_mad_i64_i32 v[2:3], s[2:3], s38, v227, v[200:201]
	s_sub_i32 s37, s37, 32
	v_mad_i64_i32 v[4:5], s[2:3], s38, v227, v[202:203]
	global_load_dwordx4 v[128:131], v[2:3], off offset:2560
	global_load_dwordx4 v[132:135], v[4:5], off offset:3584
	v_mad_i64_i32 v[2:3], s[2:3], s37, v227, v[200:201]
	s_sub_i32 s36, s36, 24
	v_mad_i64_i32 v[4:5], s[2:3], s37, v227, v[202:203]
	global_load_dwordx4 v[136:139], v[2:3], off offset:2560
	global_load_dwordx4 v[140:143], v[4:5], off offset:3584
	v_mad_i64_i32 v[2:3], s[2:3], s36, v227, v[200:201]
	s_add_i32 s35, s35, -16
	v_mad_i64_i32 v[4:5], s[2:3], s36, v227, v[202:203]
	global_load_dwordx4 v[144:147], v[2:3], off offset:2560
	global_load_dwordx4 v[148:151], v[4:5], off offset:3584
	v_mad_i64_i32 v[2:3], s[2:3], s35, v227, v[200:201]
	s_add_i32 s34, s34, -8
	v_mad_i64_i32 v[4:5], s[2:3], s35, v227, v[202:203]
	global_load_dwordx4 v[152:155], v[2:3], off offset:2560
	global_load_dwordx4 v[156:159], v[4:5], off offset:3584
	v_mad_i64_i32 v[2:3], s[2:3], s34, v227, v[200:201]
	v_mad_i64_i32 v[4:5], s[2:3], s34, v227, v[202:203]
	global_load_dwordx4 v[160:163], v[2:3], off offset:2560
	global_load_dwordx4 v[164:167], v[4:5], off offset:3584
	v_mad_i64_i32 v[2:3], s[2:3], s33, v227, v[200:201]
	v_mad_i64_i32 v[4:5], s[2:3], s33, v227, v[202:203]
	global_load_dwordx4 v[168:171], v[2:3], off offset:2560
	global_load_dwordx4 v[172:175], v[4:5], off offset:3584
.LBB0_268:
	v_mov_b32_e32 v6, v189
	ds_read_b128 v[2:5], v6 offset:512
	ds_read_b128 v[6:9], v6
	s_waitcnt lgkmcnt(0)
	v_mfma_f32_32x32x16_bf16 v[80:95], v[6:9], v[96:99], v[48:63]
	v_mov_b32_e32 v10, v191
	ds_read_b128 v[6:9], v10 offset:512
	ds_read_b128 v[10:13], v10
	v_mfma_f32_32x32x16_bf16 v[64:79], v[2:5], v[96:99], v[48:63]
	s_lshr_b32 s3, s25, 10
	s_mul_i32 s2, s3, 0xffffffdc
	s_mul_i32 s3, s3, 40
	s_sub_i32 s33, s56, s3
	s_lshr_b32 s3, s26, 10
	s_mul_i32 s35, s3, 0xffffffdc
	s_mul_i32 s3, s3, 40
	s_waitcnt lgkmcnt(0)
	v_mfma_f32_32x32x16_bf16 v[80:95], v[10:13], v[100:103], v[80:95]
	v_mov_b32_e32 v10, v204
	ds_read_b128 v[2:5], v10 offset:512
	ds_read_b128 v[10:13], v10
	s_sub_i32 s37, s56, s3
	s_lshr_b32 s3, s27, 10
	s_mul_i32 s38, s3, 0xffffffdc
	s_mul_i32 s3, s3, 40
	v_mfma_f32_32x32x16_bf16 v[64:79], v[6:9], v[100:103], v[64:79]
	s_sub_i32 s39, s56, s3
	s_lshr_b32 s3, s12, 10
	s_mul_i32 s49, s3, 0xffffffdc
	s_mul_i32 s34, s3, 40
	s_sub_i32 s36, s56, s34
	s_lshr_b32 s34, s28, 10
	s_mul_i32 s42, s34, 0xffffffdc
	s_waitcnt lgkmcnt(0)
	v_mfma_f32_32x32x16_bf16 v[80:95], v[10:13], v[104:107], v[80:95]
	v_mov_b32_e32 v10, v205
	ds_read_b128 v[6:9], v10 offset:512
	ds_read_b128 v[10:13], v10
	s_mul_i32 s34, s34, 40
	s_add_i32 s3, s13, s36
	s_sub_i32 s43, s56, s34
	s_add_i32 s50, s3, 0xffffff88
	v_mfma_f32_32x32x16_bf16 v[64:79], v[2:5], v[104:107], v[64:79]
	v_add_u32_e32 v4, s49, v193
	v_add_u32_e32 v2, 0xffffff18, v4
	ds_read2_b32 v[2:3], v2 offset1:1
	v_add_u32_e32 v5, s42, v193
	v_add_u32_e32 v176, 1, v197
	v_add_u32_e32 v4, 0xffffff20, v4
	s_add_i32 s43, s13, s43
	s_waitcnt lgkmcnt(1)
	v_mfma_f32_32x32x16_bf16 v[80:95], v[10:13], v[108:111], v[80:95]
	s_addk_i32 s43, 0xffa8
	v_add_u32_e32 v178, 3, v197
	v_add_u32_e32 v177, 2, v197
	s_lshr_b32 s47, s31, 10
	s_mul_i32 s48, s47, 0xffffffdc
	s_mul_i32 s47, s47, 40
	s_sub_i32 s47, s56, s47
	v_mfma_f32_32x32x16_bf16 v[64:79], v[6:9], v[108:111], v[64:79]
	v_add_u32_e32 v6, 0xffffff98, v5
	v_add_u32_e32 v5, 0xffffffa0, v5
	ds_read2_b32 v[6:7], v6 offset1:1
	ds_read2_b32 v[10:11], v4 offset1:1
	ds_read2_b32 v[14:15], v5 offset1:1
	v_add_u32_e32 v4, s50, v176
	s_waitcnt lgkmcnt(3)
	v_pk_add_f32 v[2:3], v[80:81], v[2:3]
	v_add_u32_e32 v5, s50, v197
	v_cmp_gt_u32_e32 vcc, 16, v4
	s_waitcnt lgkmcnt(1)
; #define LAS __attribute__((address_space(3)))
; __device__ __forceinline__ float max3f(float a, float b, float c) { float r; asm("v_max3_f32 %0, %1, %2, %3" : "=v"(r) : "v"(a), "v"(b), "v"(c)); return r; }
;     __device__ __forceinline__ void apply(f32x16& p0, f32x16& p1, int, int) const {
; #pragma unroll
;         for (int r = 0; r < 16; ++r) { const int gq = r >> 2, w = r & 3;
;             { const float v = p0[r] + tl[U[gq] + w]; p0[r] = ((unsigned)(C8[gq] + w + kcs) < 16u) ? v : -INFINITY; }
;             { const float v = p1[r] + tl[U[gq + 4] + w]; p1[r] = ((unsigned)(C8[gq + 4] + w + kcs) < 16u) ? v : -INFINITY; } }
;     }
; __device__ __forceinline__ float rowmax32(const f32x16& p0, const f32x16& p1) {
;     float a = max3f(p0[0], p0[1], p1[0]), b = max3f(p0[2], p0[3], p1[1]); a = max3f(a, p1[2], p1[3]);
; #pragma unroll
;     for (int r = 4; r < 16; r += 4) { a = max3f(a, p0[r], p0[r + 1]); b = max3f(b, p0[r + 2], p0[r + 3]); a = max3f(a, p1[r], p1[r + 1]); b = max3f(b, p1[r + 2], p1[r + 3]); }
;     return fmaxf(a, b);
; }
; __device__ __forceinline__ void qkt2(f32x16& p0, f32x16& p1, LAS const unsigned char* kslot, const bf16x8 (&qr)[4], const f32x16& negm, int r32, int hi) {
; #pragma unroll
;     for (int d0 = 0; d0 < 4; ++d0) {
;         LAS const unsigned char* kb = kslot + (2 * d0 + hi) * 1024 + ((r32 ^ (2 * d0 + hi)) * 16); asm volatile("" : "+v"(kb));
;         const bf16x8 b0 = *(LAS const bf16x8*)(kb);
;         const bf16x8 b1 = *(LAS const bf16x8*)(kb + 512);
;         if (d0 == 0) { p0 = __builtin_amdgcn_mfma_f32_32x32x16_bf16(b0, qr[0], negm, 0, 0, 0); p1 = __builtin_amdgcn_mfma_f32_32x32x16_bf16(b1, qr[0], negm, 0, 0, 0); }
;         else { p0 = __builtin_amdgcn_mfma_f32_32x32x16_bf16(b0, qr[d0], p0, 0, 0, 0); p1 = __builtin_amdgcn_mfma_f32_32x32x16_bf16(b1, qr[d0], p1, 0, 0, 0); }
;     }
; }
; template <bool HASNEXT, class Mod>
; __device__ __forceinline__ void softmax2(f32x16& p0, f32x16& p1, f32x16 (&o)[2], f32x16& negm, float& mref, float& l, LAS float* wsf, int lane, const Mod& mod, bf16x8 (&pa)[4], f32x16& n0, f32x16& n1) {
;     const int r32 = lane & 31, hi = lane >> 5;
;     mod.apply(p0, p1, r32, hi);
;     float rm = rowmax32(p0, p1);
;     if (__builtin_expect(__any(rm > THRL), 0)) {
	v_pk_add_f32 v[10:11], v[82:83], v[10:11]
	s_add_i32 s3, s13, s47
	v_cndmask_b32_e32 v4, v226, v3, vcc
	v_cmp_gt_u32_e32 vcc, 16, v5
	v_add_u32_e32 v5, s43, v176
	v_add_u32_e32 v12, s38, v193
	v_cndmask_b32_e32 v9, v226, v2, vcc
	v_pk_add_f32 v[2:3], v[64:65], v[6:7]
	v_add_u32_e32 v7, s43, v197
	v_cmp_gt_u32_e32 vcc, 16, v5
	s_add_i32 s47, s3, 0xffffff90
	s_add_i32 s39, s13, s39
	v_cndmask_b32_e32 v6, v226, v3, vcc
	v_cmp_gt_u32_e32 vcc, 16, v7
	v_add_u32_e32 v3, s50, v177
	v_add_u32_e32 v7, s43, v177
	v_cndmask_b32_e32 v13, v226, v2, vcc
	v_add_u32_e32 v2, s50, v178
	v_cmp_gt_u32_e32 vcc, 16, v2
	s_addk_i32 s39, 0xffb0
	v_add_u32_e32 v64, s47, v197
	v_cndmask_b32_e32 v2, v226, v11, vcc
	v_cmp_gt_u32_e32 vcc, 16, v3
	v_add_u32_e32 v3, s43, v178
	s_lshr_b32 s45, s30, 10
	v_cndmask_b32_e32 v5, v226, v10, vcc
	s_waitcnt lgkmcnt(0)
	v_pk_add_f32 v[10:11], v[66:67], v[14:15]
	v_cmp_gt_u32_e32 vcc, 16, v3
	v_add_u32_e32 v14, 0xffffffb8, v12
	v_subrev_u32_e32 v12, 64, v12
	v_cndmask_b32_e32 v3, v226, v11, vcc
	v_cmp_gt_u32_e32 vcc, 16, v7
	v_add_u32_e32 v7, s48, v193
	s_mul_i32 s46, s45, 0xffffffdc
	v_cndmask_b32_e32 v8, v226, v10, vcc
	v_add_u32_e32 v10, 0xffffff38, v7
	ds_read2_b32 v[10:11], v10 offset1:1
	v_add_u32_e32 v7, 0xffffff40, v7
	ds_read2_b32 v[14:15], v14 offset1:1
	ds_read2_b32 v[66:67], v7 offset1:1
	ds_read2_b32 v[80:81], v12 offset1:1
	v_add_u32_e32 v7, s47, v176
	v_cmp_gt_u32_e32 vcc, 16, v7
	s_waitcnt lgkmcnt(3)
	v_pk_add_f32 v[10:11], v[84:85], v[10:11]
	v_add_u32_e32 v7, s39, v176
	v_cndmask_b32_e32 v12, v226, v11, vcc
	v_cmp_gt_u32_e32 vcc, 16, v64
	s_mul_i32 s45, s45, 40
	s_sub_i32 s45, s56, s45
	v_cndmask_b32_e32 v64, v226, v10, vcc
	s_waitcnt lgkmcnt(2)
	v_pk_add_f32 v[10:11], v[68:69], v[14:15]
	v_add_u32_e32 v14, s39, v197
	v_cmp_gt_u32_e32 vcc, 16, v7
	v_add_u32_e32 v7, s47, v178
	v_add_u32_e32 v68, s46, v193
	v_cndmask_b32_e32 v15, v226, v11, vcc
	v_cmp_gt_u32_e32 vcc, 16, v14
	v_add_u32_e32 v14, s47, v177
	s_add_i32 s36, s13, s45
	v_cndmask_b32_e32 v65, v226, v10, vcc
	s_waitcnt lgkmcnt(1)
	v_pk_add_f32 v[10:11], v[86:87], v[66:67]
	v_cmp_gt_u32_e32 vcc, 16, v7
	s_waitcnt lgkmcnt(0)
	v_pk_add_f32 v[66:67], v[70:71], v[80:81]
	v_add_u32_e32 v69, s35, v193
	v_cndmask_b32_e32 v7, v226, v11, vcc
	v_cmp_gt_u32_e32 vcc, 16, v14
	v_add_u32_e32 v11, s39, v178
	v_add_u32_e32 v14, s39, v177
	v_cndmask_b32_e32 v10, v226, v10, vcc
	v_cmp_gt_u32_e32 vcc, 16, v11
	s_addk_i32 s36, 0xff98
	v_subrev_u32_e32 v70, 40, v69
	v_cndmask_b32_e32 v11, v226, v67, vcc
	v_cmp_gt_u32_e32 vcc, 16, v14
	v_subrev_u32_e32 v82, 32, v69
	v_add_u32_e32 v71, 0xffffff60, v68
	v_cndmask_b32_e32 v14, v226, v66, vcc
	v_add_u32_e32 v66, 0xffffff58, v68
	ds_read2_b32 v[66:67], v66 offset1:1
	ds_read2_b32 v[68:69], v70 offset1:1
	ds_read2_b32 v[80:81], v71 offset1:1
	ds_read2_b32 v[82:83], v82 offset1:1
	v_add_u32_e32 v70, s36, v176
	s_add_i32 s37, s13, s37
	v_add_u32_e32 v71, s36, v197
	s_waitcnt lgkmcnt(3)
	v_pk_add_f32 v[66:67], v[88:89], v[66:67]
	v_cmp_gt_u32_e32 vcc, 16, v70
	s_addk_i32 s37, 0xffb8
	s_waitcnt lgkmcnt(2)
	v_pk_add_f32 v[68:69], v[72:73], v[68:69]
	v_cndmask_b32_e32 v67, v226, v67, vcc
	v_cmp_gt_u32_e32 vcc, 16, v71
	v_add_u32_e32 v72, s37, v197
	s_lshr_b32 s44, s29, 10
	v_cndmask_b32_e32 v71, v226, v66, vcc
	v_add_u32_e32 v66, s37, v176
	v_cmp_gt_u32_e32 vcc, 16, v66
	v_add_u32_e32 v66, s36, v178
	s_mul_i32 s34, s44, 0xffffffdc
	v_cndmask_b32_e32 v70, v226, v69, vcc
	v_cmp_gt_u32_e32 vcc, 16, v72
	v_add_u32_e32 v72, s36, v177
	s_waitcnt lgkmcnt(0)
	v_pk_add_f32 v[74:75], v[74:75], v[82:83]
	v_cndmask_b32_e32 v73, v226, v68, vcc
	v_pk_add_f32 v[68:69], v[90:91], v[80:81]
	v_cmp_gt_u32_e32 vcc, 16, v66
	v_add_u32_e32 v80, s34, v193
	s_mul_i32 s44, s44, 40
	v_cndmask_b32_e32 v66, v226, v69, vcc
	v_cmp_gt_u32_e32 vcc, 16, v72
	v_add_u32_e32 v69, s37, v178
	v_add_u32_e32 v72, s37, v177
	v_cndmask_b32_e32 v68, v226, v68, vcc
	v_cmp_gt_u32_e32 vcc, 16, v69
	s_sub_i32 s44, s56, s44
	s_add_i32 s3, s13, s44
	v_cndmask_b32_e32 v69, v226, v75, vcc
	v_cmp_gt_u32_e32 vcc, 16, v72
	v_add_u32_e32 v81, s2, v193
	s_addk_i32 s3, 0xffa0
	v_cndmask_b32_e32 v72, v226, v74, vcc
	v_add_u32_e32 v74, 0xffffff78, v80
	ds_read2_b32 v[74:75], v74 offset1:1
	v_add_u32_e32 v82, -8, v81
	v_add_u32_e32 v80, 0xffffff80, v80
	ds_read2_b32 v[82:83], v82 offset1:1
	ds_read2_b32 v[84:85], v80 offset1:1
	ds_read2_b32 v[86:87], v81 offset1:1
	v_add_u32_e32 v80, s3, v176
	s_add_i32 s33, s13, s33
	s_waitcnt lgkmcnt(3)
	v_pk_add_f32 v[74:75], v[92:93], v[74:75]
	v_add_u32_e32 v81, s3, v197
	v_cmp_gt_u32_e32 vcc, 16, v80
	s_sub_i32 s33, s33, 64
	s_waitcnt lgkmcnt(2)
	v_pk_add_f32 v[76:77], v[76:77], v[82:83]
	v_cndmask_b32_e32 v75, v226, v75, vcc
	v_cmp_gt_u32_e32 vcc, 16, v81
	v_add_u32_e32 v81, s33, v197
	s_waitcnt lgkmcnt(1)
	v_pk_add_f32 v[82:83], v[94:95], v[84:85]
	v_cndmask_b32_e32 v80, v226, v74, vcc
	v_add_u32_e32 v74, s33, v176
	v_cmp_gt_u32_e32 vcc, 16, v74
	v_add_u32_e32 v74, s3, v178
	s_nop 0
	v_cndmask_b32_e32 v77, v226, v77, vcc
	v_cmp_gt_u32_e32 vcc, 16, v81
	s_nop 1
	v_cndmask_b32_e32 v81, v226, v76, vcc
	v_add_u32_e32 v76, s3, v177
	v_cmp_gt_u32_e32 vcc, 16, v74
	s_nop 1
	v_cndmask_b32_e32 v74, v226, v83, vcc
	v_cmp_gt_u32_e32 vcc, 16, v76
	s_nop 1
	v_cndmask_b32_e32 v76, v226, v82, vcc
	s_waitcnt lgkmcnt(0)
	v_pk_add_f32 v[82:83], v[78:79], v[86:87]
	v_add_u32_e32 v78, s33, v178
	v_add_u32_e32 v79, s33, v177
	v_cmp_gt_u32_e32 vcc, 16, v78
	s_nop 1
	v_cndmask_b32_e32 v78, v226, v83, vcc
	v_cmp_gt_u32_e32 vcc, 16, v79
	v_max3_f32 v83, v5, v2, v6
	s_nop 0
	v_max3_f32 v83, v83, v10, v7
	s_nop 0
	v_cndmask_b32_e32 v79, v226, v82, vcc
	v_max3_f32 v82, v9, v4, v13
	v_max3_f32 v83, v83, v14, v11
	s_nop 0
	v_max3_f32 v82, v82, v8, v3
	v_max3_f32 v83, v83, v68, v66
	s_nop 0
	v_max3_f32 v82, v82, v64, v12
	v_max3_f32 v83, v83, v72, v69
	s_nop 0
	v_max3_f32 v82, v82, v65, v15
	v_max3_f32 v83, v83, v76, v74
	s_nop 0
	v_max3_f32 v82, v82, v71, v67
	v_max3_f32 v83, v83, v79, v78
	s_nop 0
	v_max3_f32 v82, v82, v73, v70
	v_max_f32_e32 v83, v83, v83
	v_max3_f32 v82, v82, v80, v75
	s_nop 0
	v_max3_f32 v82, v82, v81, v77
	s_nop 0
	v_max_f32_e32 v82, v82, v82
	v_max_f32_e32 v82, v82, v83
	v_cmp_lt_f32_e32 vcc, s90, v82
	s_cbranch_vccnz .LBB0_270
